# baseline (speedup 1.0000x reference)
; __device__ __forceinline__ float bf2f(u16 h) { return __uint_as_float(((unsigned)h) << 16); }
; __device__ __forceinline__ float siluf_(float v) { return v * __builtin_amdgcn_rcpf(1.f + __expf(-v)); }
; template <int DUMMY>
; __device__ void ssd_item(const Params& p, int item) {
;     ...
;     {
;       float dec = __expf(cs[63]);
; #pragma unroll
;       for (int j = 0; j < 2; ++j) {
;         accS[j][0] *= dec; accS[j][1] *= dec; accS[j][2] *= dec; accS[j][3] *= dec;
;       }
; #pragma unroll
;       for (int ks = 0; ks < 2; ++ks) {
;         bf16x8 a = *(const bf16x8*)(xwT + (pf * 16 + fr) * 72 + ks * 32 + g4 * 8);
; #pragma unroll
;         for (int j = 0; j < 2; ++j) {
;           bf16x8 bb = *(const bf16x8*)(BTs + ((nf0 + j) * 16 + fr) * 72 + ks * 32 + g4 * 8);
;           accS[j] = __builtin_amdgcn_mfma_f32_16x16x32_bf16(a, bb, accS[j], 0, 0, 0);
;         }
;       }
;     }
;     __builtin_amdgcn_s_setprio(0);
;     RAW_BARRIER();
;     __builtin_amdgcn_s_setprio(1);
;     {
;       f32x4 yd = {0.f, 0.f, 0.f, 0.f}, yo = {0.f, 0.f, 0.f, 0.f};
; #pragma unroll
;       for (int ks = 0; ks < 2; ++ks) {
;         bf16x8 a = *(const bf16x8*)(Gs + (lf * 16 + fr) * 72 + ks * 32 + g4 * 8);
;         bf16x8 bb = *(const bf16x8*)(xdT + (pf * 16 + fr) * 72 + ks * 32 + g4 * 8);
;         yd = __builtin_amdgcn_mfma_f32_16x16x32_bf16(a, bb, yd, 0, 0, 0);
;       }
; #pragma unroll
;       for (int ks = 0; ks < 4; ++ks) {
;         bf16x8 a = *(const bf16x8*)(Cs + (lf * 16 + fr) * 136 + ks * 32 + g4 * 8);
;         bf16x8 bb = *(const bf16x8*)(Sb + (pf * 16 + fr) * 136 + ks * 32 + g4 * 8);
;         yo = __builtin_amdgcn_mfma_f32_16x16x32_bf16(a, bb, yo, 0, 0, 0);
;       }
;       __builtin_amdgcn_s_setprio(0);
;       bf16x4 xs4 = *(const bf16x4*)(xT + (pf * 16 + fr) * 72 + lf * 16 + g4 * 4);
; #pragma unroll
;       for (int r = 0; r < 4; ++r) {
;         int l_ = lf * 16 + g4 * 4 + r;
;         float y = yd[r] + __expf(cs[l_]) * yo[r] + Dh * bf2f((u16)xs4[r]);
;         y *= siluf_(bf2f(zcur[r]));
;         ytile[l_ * 36 + pf * 16 + fr] = f2bf(y);
;         float sq = row16_sum(y * y);
;         if (fr == 0) sqs[wid * 16 + g4 * 4 + r] = sq;
;       }
.LBB0_1067:
	s_or_b64 exec, exec, s[30:31]
	v_mov_b32_e32 v33, s52
	ds_read_b32 v100, v33 offset:252
	ds_write_b16 v131, v32
	ds_read_b128 v[32:35], v134 offset:57856
	s_waitcnt lgkmcnt(7)
	ds_read_b128 v[36:39], v136 offset:34816
	ds_read_b128 v[178:181], v138 offset:34816
	ds_read_b128 v[182:185], v134 offset:57920
	ds_read_b128 v[186:189], v136 offset:34880
	s_waitcnt lgkmcnt(6)
	v_mul_f32_e32 v100, 0x3fb8aa3b, v100
	v_exp_f32_e32 v100, v100
	s_nop 0
	v_pk_mul_f32 v[6:7], v[6:7], v[100:101] op_sel_hi:[1,0]
	v_pk_mul_f32 v[4:5], v[4:5], v[100:101] op_sel_hi:[1,0]
	v_pk_mul_f32 v[2:3], v[2:3], v[100:101] op_sel_hi:[1,0]
	v_pk_mul_f32 v[0:1], v[0:1], v[100:101] op_sel_hi:[1,0]
	s_waitcnt lgkmcnt(3)
	v_mfma_f32_16x16x32_bf16 v[4:7], v[32:35], v[36:39], v[4:7]
	ds_read_b128 v[36:39], v138 offset:34880
	s_waitcnt lgkmcnt(3)
	v_mfma_f32_16x16x32_bf16 v[0:3], v[32:35], v[178:181], v[0:3]
	s_waitcnt lgkmcnt(1)
	v_mfma_f32_16x16x32_bf16 v[4:7], v[182:185], v[186:189], v[4:7]
	s_waitcnt lgkmcnt(0)
	v_mfma_f32_16x16x32_bf16 v[0:3], v[182:185], v[36:39], v[0:3]
	s_setprio 0
	s_waitcnt lgkmcnt(0)
	s_barrier
	s_setprio 1
	ds_read_b128 v[32:35], v42
	v_add3_u32 v100, s78, v162, v161
	ds_read_b128 v[36:39], v100
	ds_read_b128 v[178:181], v132
	ds_read_b128 v[182:185], v42 offset:64
	ds_read_b128 v[186:189], v100 offset:64
	v_add3_u32 v101, s53, v160, v161
	s_waitcnt lgkmcnt(3)
	v_mfma_f32_16x16x32_bf16 v[32:35], v[32:35], v[36:39], 0
	ds_read_b128 v[36:39], v101
	ds_read_b128 v[190:193], v132 offset:64
	ds_read_b128 v[194:197], v101 offset:64
	s_waitcnt lgkmcnt(2)
	v_mfma_f32_16x16x32_bf16 v[178:181], v[178:181], v[36:39], 0
	ds_read_b128 v[36:39], v42 offset:128
	ds_read_b128 v[198:201], v42 offset:192
	v_mfma_f32_16x16x32_bf16 v[32:35], v[182:185], v[186:189], v[32:35]
	ds_read_b128 v[182:185], v100 offset:128
	ds_read_b128 v[186:189], v100 offset:192
	s_waitcnt lgkmcnt(1)
	v_mfma_f32_16x16x32_bf16 v[32:35], v[36:39], v[182:185], v[32:35]
	s_waitcnt lgkmcnt(0)
	v_mfma_f32_16x16x32_bf16 v[36:39], v[198:201], v[186:189], v[32:35]
	v_mfma_f32_16x16x32_bf16 v[32:35], v[190:193], v[194:197], v[178:181]
	s_setprio 0
	v_add_u32_e32 v42, s77, v160
	v_add3_u32 v42, v42, v163, v164
	ds_read_b32 v177, v87
	ds_read_b64 v[100:101], v42
	s_waitcnt vmcnt(14)
	v_lshlrev_b32_e32 v42, 16, v167
	v_mul_f32_e32 v167, 0xbfb8aa3b, v42
	v_exp_f32_e32 v167, v167
	s_waitcnt lgkmcnt(1)
	v_mul_f32_e32 v177, 0x3fb8aa3b, v177
	v_exp_f32_e32 v177, v177
	v_add_f32_e32 v167, 1.0, v167
	v_rcp_f32_e32 v167, v167
	v_fma_f32 v32, v36, v177, v32
	s_waitcnt lgkmcnt(0)
	v_lshlrev_b32_e32 v36, 16, v100
	v_fmac_f32_e32 v32, v43, v36
	v_mul_f32_e32 v36, v167, v42
	v_mul_f32_e32 v32, v36, v32
	v_cvt_pk_bf16_f32 v36, v32, s0
	ds_write_b16 v123, v36
	v_mul_f32_e32 v36, v32, v32
	s_nop 1
	v_mov_b32_dpp v36, v36 quad_perm:[1,0,3,2] row_mask:0xf bank_mask:0xf bound_ctrl:1
	v_fmac_f32_e32 v36, v32, v32
	s_nop 1
	v_add_f32_dpp v32, v36, v36 quad_perm:[2,3,0,1] row_mask:0xf bank_mask:0xf bound_ctrl:1
	s_nop 1
	v_add_f32_dpp v32, v32, v32 row_half_mirror row_mask:0xf bank_mask:0xf bound_ctrl:1
	s_nop 1
	v_mov_b32_dpp v36, v32 row_mirror row_mask:0xf bank_mask:0xf bound_ctrl:1
	s_and_saveexec_b64 s[30:31], s[0:1]
	v_add_f32_e32 v32, v32, v36
	ds_write_b32 v122, v32
	s_or_b64 exec, exec, s[30:31]
	s_waitcnt vmcnt(13)
	v_lshlrev_b32_e32 v166, 16, v166
	ds_read_b32 v32, v87 offset:4
	v_mul_f32_e32 v36, 0xbfb8aa3b, v166
	v_exp_f32_e32 v36, v36
	v_and_b32_e32 v167, 0xffff0000, v100
	s_waitcnt lgkmcnt(0)
	v_mul_f32_e32 v32, 0x3fb8aa3b, v32
	v_add_f32_e32 v36, 1.0, v36
	v_exp_f32_e32 v32, v32
	v_rcp_f32_e32 v42, v36
	v_fma_f32 v36, v37, v32, v33
	v_pk_mul_f32 v[32:33], v[42:43], v[166:167]
	s_nop 0
	v_add_f32_e32 v33, v33, v36
	v_mul_f32_e32 v32, v32, v33
	v_cvt_pk_bf16_f32 v33, v32, s0
	v_mul_f32_e32 v36, v32, v32
	ds_write_b16 v123, v33 offset:72
	s_nop 0
	v_mov_b32_dpp v33, v36 quad_perm:[1,0,3,2] row_mask:0xf bank_mask:0xf bound_ctrl:1
	v_fmac_f32_e32 v33, v32, v32
	s_nop 1
	v_add_f32_dpp v32, v33, v33 quad_perm:[2,3,0,1] row_mask:0xf bank_mask:0xf bound_ctrl:1
	s_nop 1
	v_add_f32_dpp v32, v32, v32 row_half_mirror row_mask:0xf bank_mask:0xf bound_ctrl:1
	s_nop 1
	v_mov_b32_dpp v33, v32 row_mirror row_mask:0xf bank_mask:0xf bound_ctrl:1
	s_and_saveexec_b64 s[30:31], s[0:1]
	v_add_f32_e32 v32, v32, v33
	ds_write_b32 v122, v32 offset:4
	s_or_b64 exec, exec, s[30:31]
	ds_read_b32 v33, v87 offset:8
	s_waitcnt vmcnt(12)
	v_lshlrev_b32_e32 v32, 16, v165
	v_mul_f32_e32 v36, 0xbfb8aa3b, v32
	v_exp_f32_e32 v36, v36
	s_waitcnt lgkmcnt(0)
; template <int DUMMY>
; __device__ void ssd_item(const Params& p, int item) {
;     ...
;     for (int r = 0; r < 4; ++r) zcur[r] = znext[r];
;     if (c > 1) {
;       const size_t yi = (tb + (c - 2) * 64 + (tid >> 3)) * 4096 + h * 64 + ph * 32 + (tid & 7) * 4;
;       *(i32x2*)(zyo + (yi & omask)) = ypend;
;     }
;     if (c + 1 < 128) {
;       load_raw(c + 1);
;       const size_t zn = zbase + (size_t)64 * 4096;
; #pragma unroll
;       for (int r = 0; r < 4; ++r) znext[r] = zy[zn + (size_t)r * 4096];
;       if (wid == 0) {
;         float dt_use = dt_n;
;         if (c + 2 < 128) dt_n = dtb[(tb + (c + 2) * 64 + lane) * 64 + h];
;         write_cs(dt_use, nxt3);
;       }
	v_mul_f32_e32 v33, 0x3fb8aa3b, v33
	v_exp_f32_e32 v37, v33
	v_add_f32_e32 v33, 1.0, v36
	v_rcp_f32_e32 v42, v33
	v_lshlrev_b32_e32 v33, 16, v101
	v_fma_f32 v34, v38, v37, v34
	v_pk_mul_f32 v[32:33], v[42:43], v[32:33]
	s_nop 0
	v_add_f32_e32 v33, v33, v34
	v_mul_f32_e32 v32, v32, v33
	v_cvt_pk_bf16_f32 v33, v32, s0
	v_mul_f32_e32 v34, v32, v32
	ds_write_b16 v123, v33 offset:144
	s_nop 0
	v_mov_b32_dpp v33, v34 quad_perm:[1,0,3,2] row_mask:0xf bank_mask:0xf bound_ctrl:1
	v_fmac_f32_e32 v33, v32, v32
	s_nop 1
	v_add_f32_dpp v32, v33, v33 quad_perm:[2,3,0,1] row_mask:0xf bank_mask:0xf bound_ctrl:1
	s_nop 1
	v_add_f32_dpp v32, v32, v32 row_half_mirror row_mask:0xf bank_mask:0xf bound_ctrl:1
	s_nop 1
	v_mov_b32_dpp v33, v32 row_mirror row_mask:0xf bank_mask:0xf bound_ctrl:1
	s_and_saveexec_b64 s[30:31], s[0:1]
	v_add_f32_e32 v32, v32, v33
	ds_write_b32 v122, v32 offset:8
	s_or_b64 exec, exec, s[30:31]
	ds_read_b32 v33, v87 offset:12
	s_waitcnt vmcnt(11)
	v_lshlrev_b32_e32 v32, 16, v75
	v_mul_f32_e32 v34, 0xbfb8aa3b, v32
	v_exp_f32_e32 v34, v34
	s_waitcnt lgkmcnt(0)
	v_mul_f32_e32 v33, 0x3fb8aa3b, v33
	v_exp_f32_e32 v36, v33
	v_add_f32_e32 v33, 1.0, v34
	v_rcp_f32_e32 v42, v33
	v_and_b32_e32 v33, 0xffff0000, v101
	v_fmac_f32_e32 v35, v39, v36
	v_pk_mul_f32 v[32:33], v[42:43], v[32:33]
	s_nop 0
	v_add_f32_e32 v33, v33, v35
	v_mul_f32_e32 v32, v32, v33
	v_cvt_pk_bf16_f32 v33, v32, s0
	v_mul_f32_e32 v34, v32, v32
	ds_write_b16 v123, v33 offset:216
	s_nop 0
	v_mov_b32_dpp v33, v34 quad_perm:[1,0,3,2] row_mask:0xf bank_mask:0xf bound_ctrl:1
	v_fmac_f32_e32 v33, v32, v32
	s_nop 1
	v_add_f32_dpp v32, v33, v33 quad_perm:[2,3,0,1] row_mask:0xf bank_mask:0xf bound_ctrl:1
	s_nop 1
	v_add_f32_dpp v32, v32, v32 row_half_mirror row_mask:0xf bank_mask:0xf bound_ctrl:1
	s_nop 1
	v_mov_b32_dpp v33, v32 row_mirror row_mask:0xf bank_mask:0xf bound_ctrl:1
	s_and_saveexec_b64 s[30:31], s[0:1]
	v_add_f32_e32 v32, v32, v33
	ds_write_b32 v122, v32 offset:12
	s_or_b64 exec, exec, s[30:31]
	s_add_u32 s70, s70, 0x40000
	s_addc_u32 s71, s71, 0
	s_mov_b64 s[30:31], 0x4000
	s_add_i32 s76, s76, 1
	s_waitcnt vmcnt(4)
	v_perm_b32 v42, v40, v176, s94
	v_perm_b32 v100, v176, v175, s94
	v_perm_b32 v101, v175, v173, s94
	v_perm_b32 v173, v173, v174, s94
	v_perm_b32 v171, v172, v171, s94
	v_lshl_add_u64 v[84:85], v[84:85], 0, s[60:61]
	v_add_u32_e32 v86, 64, v86
	v_lshl_add_u64 v[92:93], v[92:93], 0, s[30:31]
	v_lshl_add_u64 v[94:95], v[94:95], 0, s[62:63]
	v_lshl_add_u64 v[96:97], v[96:97], 0, s[62:63]
	s_cmp_eq_u32 s70, 0x1f00000
	v_lshl_add_u64 v[98:99], v[98:99], 0, s[60:61]
	s_waitcnt vmcnt(0)
	v_mov_b32_e32 v118, v255
	s_cbranch_scc1 .LBB0_1077
	s_waitcnt vmcnt(0)
	v_mov_b32_e32 v75, v49
	v_mov_b32_e32 v165, v168
	v_mov_b32_e32 v166, v169
	v_mov_b32_e32 v167, v170
	v_lshl_add_u64 v[224:225], v[78:79], 0, s[70:71]
	v_lshl_add_u64 v[226:227], v[80:81], 0, s[70:71]
	v_add_co_u32_e32 v224, vcc, 0x100000, v224
	s_nop 1
	v_addc_co_u32_e32 v225, vcc, 0, v225, vcc
	v_add_co_u32_e32 v226, vcc, 0x100000, v226
	s_nop 1
	v_addc_co_u32_e32 v227, vcc, 0, v227, vcc
	global_load_dword v228, v[224:225], off
	global_load_dword v228, v[224:225], off offset:2048
	global_load_dword v228, v[226:227], off
	global_load_dword v228, v[226:227], off offset:2048
	v_add_u32_e32 v224, 61, v86
	v_mov_b32_e32 v225, v41
	v_lshl_add_u64 v[224:225], s[64:65], 0, v[224:225]
	v_mad_u64_u32 v[226:227], s[72:73], v224, s86, v[66:67]
	v_mad_i32_i24 v227, v225, s86, v227
	global_load_ushort v228, v[226:227], off
	v_add_co_u32_e32 v226, vcc, 0x3000, v226
	s_nop 1
	v_addc_co_u32_e32 v227, vcc, 0, v227, vcc
	global_load_ushort v228, v[226:227], off
	v_add_co_u32_e32 v226, vcc, 0x3000, v226
	s_nop 1
	v_addc_co_u32_e32 v227, vcc, 0, v227, vcc
	global_load_ushort v228, v[226:227], off
	v_add_co_u32_e32 v226, vcc, 0x3000, v226
	s_nop 1
	v_addc_co_u32_e32 v227, vcc, 0, v227, vcc
	global_load_ushort v228, v[226:227], off
	v_lshl_add_u64 v[224:225], v[84:85], 0, s[60:61]
	v_lshl_add_u64 v[224:225], s[42:43], 0, v[224:225]
	v_add_co_u32_e32 v226, vcc, 0xb280000, v224
	s_nop 1
	v_addc_co_u32_e32 v227, vcc, 0, v225, vcc
	global_load_ushort v228, v[226:227], off
	v_add_co_u32_e32 v226, vcc, 0xb282000, v224
	s_nop 1
	v_addc_co_u32_e32 v227, vcc, 0, v225, vcc
	global_load_ushort v228, v[226:227], off
	v_add_co_u32_e32 v226, vcc, 0xb284000, v224
	s_nop 1
	v_addc_co_u32_e32 v227, vcc, 0, v225, vcc
	global_load_ushort v228, v[226:227], off
	v_add_co_u32_e32 v226, vcc, 0xb286000, v224
	s_nop 1
	v_addc_co_u32_e32 v227, vcc, 0, v225, vcc
	global_load_ushort v228, v[226:227], off
	s_and_saveexec_b64 s[72:73], s[4:5]
	v_lshl_add_u64 v[224:225], s[42:43], 0, v[92:93]
	v_add_co_u32_e32 v224, vcc, 0x4000, v224
	s_nop 1
	v_addc_co_u32_e32 v225, vcc, 0, v225, vcc
	global_load_dword v228, v[224:225], off
	s_or_b64 exec, exec, s[72:73]
	s_branch .LBB0_1033
